# grid barrier: the L1 acquire invalidate is issued right after the arrival atomic (before the spin) instead of after the release is observed
# speedup vs baseline: 1.0350x; 1.0057x over previous
.LBB0_705:
	s_or_b64 exec, exec, s[2:3]
	v_cvt_f32_u32_e32 v5, v3
	s_waitcnt vmcnt(0)
	buffer_inv sc1
	v_readfirstlane_b32 s2, v4
	v_sub_u32_e32 v4, 0, v3
	v_rcp_iflag_f32_e32 v5, v5
	v_add_u32_e32 v6, s2, v1
	v_mul_f32_e32 v5, 0x4f7ffffe, v5
	v_cvt_u32_f32_e32 v5, v5
	v_mul_lo_u32 v1, v4, v5
	v_mul_hi_u32 v1, v5, v1
	v_add_u32_e32 v1, v5, v1
	v_mul_hi_u32 v1, v6, v1
	v_mul_lo_u32 v4, v1, v3
	v_sub_u32_e32 v4, v6, v4
	v_add_u32_e32 v5, 1, v1
	v_cmp_ge_u32_e32 vcc, v4, v3
	s_nop 1
	v_cndmask_b32_e32 v1, v1, v5, vcc
	v_sub_u32_e32 v5, v4, v3
	v_cndmask_b32_e32 v4, v4, v5, vcc
	v_add_u32_e32 v5, 1, v1
	v_cmp_ge_u32_e32 vcc, v4, v3
	v_add_u32_e32 v4, 1, v6
	s_nop 0
	v_cndmask_b32_e32 v1, v1, v5, vcc
	v_mul_lo_u32 v5, v3, v1
	v_add_u32_e32 v3, v5, v3
	v_cmp_ne_u32_e32 vcc, v4, v3
	s_and_saveexec_b64 s[2:3], vcc
	s_xor_b64 s[2:3], exec, s[2:3]
	s_cbranch_execz .LBB0_719
	v_readlane_b32 s4, v254, 54
	v_readlane_b32 s5, v254, 55
	s_waitcnt lgkmcnt(0)
	s_nop 3
	global_load_dword v2, v0, s[4:5] sc1
	s_waitcnt vmcnt(0)
	v_cmp_eq_u32_e32 vcc, v2, v1
	s_and_saveexec_b64 s[4:5], vcc
	s_cbranch_execz .LBB0_718
	s_mov_b32 s17, 1
	s_mov_b64 s[6:7], 0
	s_branch .LBB0_709

.LBB0_718:
	s_or_b64 exec, exec, s[4:5]
	s_waitcnt vmcnt(0)
	s_waitcnt vmcnt(0)

.Lbar_local:
	s_mov_b64 s[2:3], exec
	v_mbcnt_lo_u32_b32 v1, s2, 0
	v_mbcnt_hi_u32_b32 v1, s3, v1
	v_cmp_eq_u32_e32 vcc, 0, v1
	s_waitcnt vmcnt(0)
	s_and_saveexec_b64 s[4:5], vcc
	s_cbranch_execz .LBB0_143
	s_bcnt1_i32_b64 s2, s[2:3]
	v_mov_b32_e32 v1, s2
	v_readlane_b32 s2, v254, 54
	v_readlane_b32 s3, v254, 55
	s_nop 4
	global_atomic_add v0, v1, s[2:3]
	s_branch .LBB0_143
